# A1 attention output epilogue: 16 dwordx2 row stores widened to 8 dwordx4 via v_permlane32_swap pairs (strategy: pair narrow stores into wide ones)
# baseline (speedup 1.0000x reference)
; template <int NHQ, int NHKV>
; DI void attn_phase_l1(const u16* __restrict__ Q, const u16* __restrict__ K, const u16* __restrict__ Vt, u16* __restrict__ O, const float* __restrict__ qg, char* smem, const int wv) {
;     ...
;       if (j == NT - 1) {
;         const char* svl = vb0 + (j & 1) * VBYTES + r32 * VSTR + hh * 16;
;         bf16x8 vf[4];
; #pragma unroll
;         for (int d = 0; d < 4; ++d) vf[d] = *(const bf16x8*)(svl + d * 32 * VSTR);
; #pragma unroll
;         for (int d = 0; d < 4; ++d) o[d] = __builtin_amdgcn_mfma_f32_32x32x16_bf16(vf[d], pb[0], o[d], 0, 0, 0);
;       } else {
;         constexpr int NQK = 2 * NS, NM = NQK + 16, RING = 8;
;         const char* sk = kb0 + ((j + 1) & 1) * KBYTES + r32 * KSTR + hh * 16;
;         const char* sv = vb0 + (j & 1) * VBYTES + r32 * VSTR + hh * 16;
;         bf16x8 ring[RING];
;         unsigned w_[16]; f32x2 ps2 = {0.f, 0.f};
;     ...
; #pragma unroll
;         for (int i = 0; i < 16; ++i) { s0[i] = 0.f; s1[i] = 0.f; }
; #pragma unroll
;         for (int i = 0; i < RING; ++i) B_FRAG(ring[i], i);
; #pragma unroll
;         for (int i = 0; i < NM; ++i) {
;           if (i < NQK) {
;             if (i & 1) s1 = __builtin_amdgcn_mfma_f32_32x32x16_bf16(ring[i % RING], qf[i >> 1], s1, 0, 0, 0);
;             else       s0 = __builtin_amdgcn_mfma_f32_32x32x16_bf16(ring[i % RING], qf[i >> 1], s0, 0, 0, 0);
;           } else {
;             o[(i - NQK) & 3] = __builtin_amdgcn_mfma_f32_32x32x16_bf16(ring[i % RING], pb[(i - NQK) >> 2], o[(i - NQK) & 3], 0, 0, 0);
;           }
;           if (i + RING < NM) B_FRAG(ring[i % RING], i + RING);
;           if (i >= NQK + 2) {
;             const int g = i - NQK - 2;
;             f32x2 v;
;             if (g < 8) { v[0] = __builtin_amdgcn_exp2f(s0[2 * g]); v[1] = __builtin_amdgcn_exp2f(s0[2 * g + 1]); }
;             else       { v[0] = __builtin_amdgcn_exp2f(s1[2 * (g - 8)]); v[1] = __builtin_amdgcn_exp2f(s1[2 * (g - 8) + 1]); }
;             ps2 += v; w_[g] = cvtpk(v[0], v[1]);
;           }
;           __builtin_amdgcn_sched_barrier(0);
;         }
; #pragma unroll
;         for (int g = 14; g < 16; ++g) { f32x2 v; v[0] = __builtin_amdgcn_exp2f(s1[2 * (g - 8)]); v[1] = __builtin_amdgcn_exp2f(s1[2 * (g - 8) + 1]); ps2 += v; w_[g] = cvtpk(v[0], v[1]); }
;     ...
;         if (j + 1 == NT - 1) {
;           ps2 = f32x2{0.f, 0.f};
; #pragma unroll
.LBB0_1215:
	v_add_u32_e32 v64, s20, v204
	v_mov_b32_e32 v81, v145
	v_mov_b32_e32 v82, v146
	v_mov_b32_e32 v83, v147
	v_mov_b32_e32 v93, v157
	v_mov_b32_e32 v94, v158
	v_mov_b32_e32 v95, v159
	v_mov_b32_e32 v89, v153
	v_mov_b32_e32 v90, v154
	v_mov_b32_e32 v91, v155
	v_mov_b32_e32 v85, v149
	v_mov_b32_e32 v86, v150
	v_mov_b32_e32 v87, v151
	s_waitcnt vmcnt(1)
	ds_write_b128 v64, v[136:139] offset:34816
	s_waitcnt vmcnt(0)
	ds_write_b128 v64, v[140:143] offset:44032
	v_add_u32_e32 v144, s26, v205
	ds_read_b128 v[64:67], v144
	ds_read_b128 v[128:131], v144 offset:32
	ds_read_b128 v[132:135], v144 offset:64
	ds_read_b128 v[136:139], v144 offset:96
	ds_read_b128 v[140:143], v144 offset:128
	s_waitcnt lgkmcnt(4)
	v_mfma_f32_32x32x16_bf16 v[64:79], v[64:67], v[100:103], 0
	ds_read_b128 v[100:103], v144 offset:160
	s_waitcnt lgkmcnt(4)
	v_mfma_f32_32x32x16_bf16 v[64:79], v[128:131], v[108:111], v[64:79]
	ds_read_b128 v[108:111], v144 offset:192
	s_waitcnt lgkmcnt(4)
	v_mfma_f32_32x32x16_bf16 v[64:79], v[132:135], v[96:99], v[64:79]
	ds_read_b128 v[96:99], v144 offset:224
	s_waitcnt lgkmcnt(4)
	v_mfma_f32_32x32x16_bf16 v[64:79], v[136:139], v[104:107], v[64:79]
	ds_read_b128 v[104:107], v206 offset:53248
	s_waitcnt lgkmcnt(4)
	v_mfma_f32_32x32x16_bf16 v[64:79], v[140:143], v[116:119], v[64:79]
	ds_read_b128 v[116:119], v206 offset:57856
	ds_read_b128 v[128:131], v206 offset:62464
	s_waitcnt lgkmcnt(5)
	v_mfma_f32_32x32x16_bf16 v[64:79], v[100:103], v[120:123], v[64:79]
	ds_read_b128 v[100:103], v207 offset:32256
	ds_read_b128 v[120:123], v206 offset:53280
	s_waitcnt lgkmcnt(6)
	v_mfma_f32_32x32x16_bf16 v[64:79], v[108:111], v[112:115], v[64:79]
	ds_read_b128 v[108:111], v206 offset:57888
	ds_read_b128 v[112:115], v206 offset:62496
	s_waitcnt lgkmcnt(7)
	v_mfma_f32_32x32x16_bf16 v[64:79], v[96:99], v[124:127], v[64:79]
	s_nop 11
	ds_read_b128 v[72:75], v207 offset:32288
	ds_read_b128 v[76:79], v206 offset:53312
	s_waitcnt lgkmcnt(8)
	v_mfma_f32_32x32x16_bf16 v[48:63], v[104:107], v[80:83], v[48:63]
	ds_read_b128 v[96:99], v206 offset:57920
	s_waitcnt lgkmcnt(8)
	v_mfma_f32_32x32x16_bf16 v[32:47], v[116:119], v[80:83], v[32:47]
	v_exp_f32_e32 v64, v64
	v_exp_f32_e32 v65, v65
	ds_read_b128 v[104:107], v206 offset:62528
	s_waitcnt lgkmcnt(8)
	v_mfma_f32_32x32x16_bf16 v[16:31], v[128:131], v[80:83], v[16:31]
	v_add_f32_e64 v124, v64, 0
	v_add_f32_e64 v125, v65, 0
	v_cvt_pk_bf16_f32 v64, v64, v65
	v_exp_f32_e32 v66, v66
	v_exp_f32_e32 v67, v67
	ds_read_b128 v[116:119], v207 offset:32320
	s_waitcnt lgkmcnt(8)
	v_mfma_f32_32x32x16_bf16 v[0:15], v[100:103], v[80:83], v[0:15]
	v_add_f32_e64 v124, v66, v124
	v_add_f32_e64 v125, v67, v125
	v_cvt_pk_bf16_f32 v65, v66, v67
	v_exp_f32_e32 v66, v68
	v_exp_f32_e32 v67, v69
	ds_read_b128 v[80:83], v206 offset:53344
	s_waitcnt lgkmcnt(8)
	v_mfma_f32_32x32x16_bf16 v[48:63], v[120:123], v[84:87], v[48:63]
	v_add_f32_e64 v100, v66, v124
	v_add_f32_e64 v101, v67, v125
	v_cvt_pk_bf16_f32 v66, v66, v67
	v_exp_f32_e32 v102, v70
	v_exp_f32_e32 v103, v71
	ds_read_b128 v[68:71], v206 offset:57952
	s_waitcnt lgkmcnt(8)
	v_mfma_f32_32x32x16_bf16 v[32:47], v[108:111], v[84:87], v[32:47]
	v_add_f32_e64 v120, v102, v100
	v_add_f32_e64 v121, v103, v101
	v_cvt_pk_bf16_f32 v67, v102, v103
	ds_read_b128 v[100:103], v206 offset:62560
	s_waitcnt lgkmcnt(8)
	v_mfma_f32_32x32x16_bf16 v[16:31], v[112:115], v[84:87], v[16:31]
	ds_read_b128 v[108:111], v207 offset:32352
	s_waitcnt lgkmcnt(8)
	v_mfma_f32_32x32x16_bf16 v[0:15], v[72:75], v[84:87], v[0:15]
	s_waitcnt lgkmcnt(7)
	v_mfma_f32_32x32x16_bf16 v[48:63], v[76:79], v[88:91], v[48:63]
	s_waitcnt lgkmcnt(6)
	v_mfma_f32_32x32x16_bf16 v[32:47], v[96:99], v[88:91], v[32:47]
	s_waitcnt lgkmcnt(5)
	v_mfma_f32_32x32x16_bf16 v[16:31], v[104:107], v[88:91], v[16:31]
	s_waitcnt lgkmcnt(4)
	v_mfma_f32_32x32x16_bf16 v[0:15], v[116:119], v[88:91], v[0:15]
	s_waitcnt lgkmcnt(3)
	v_mfma_f32_32x32x16_bf16 v[48:63], v[80:83], v[92:95], v[48:63]
	s_waitcnt lgkmcnt(2)
	v_mfma_f32_32x32x16_bf16 v[32:47], v[68:71], v[92:95], v[32:47]
	s_waitcnt lgkmcnt(1)
	v_mfma_f32_32x32x16_bf16 v[16:31], v[100:103], v[92:95], v[16:31]
	s_waitcnt lgkmcnt(0)
	v_mfma_f32_32x32x16_bf16 v[0:15], v[108:111], v[92:95], v[0:15]
	s_waitcnt lgkmcnt(0)
	s_barrier
	v_add_f32_e32 v68, v120, v121
	v_add_f32_e32 v84, v176, v68
	ds_read_b128 v[68:71], v211 offset:34816
	ds_read_b128 v[72:75], v211 offset:39424
	ds_read_b128 v[76:79], v211 offset:44032
	ds_read_b128 v[80:83], v211 offset:48640
	v_mov_b32_e32 v85, v84
	s_nop 1
	v_permlane32_swap_b32_e32 v84, v85
	s_waitcnt lgkmcnt(3)
	v_mfma_f32_32x32x16_bf16 v[48:63], v[68:71], v[64:67], v[48:63]
	v_add_f32_e32 v68, v84, v85
	v_div_scale_f32 v69, s[20:21], v68, v68, 1.0
	v_rcp_f32_e32 v70, v69
	s_waitcnt lgkmcnt(0)
	s_barrier
; DI unsigned cvtpk(float lo, float hi) { f32x2 v = {lo, hi}; return __builtin_bit_cast(unsigned, __builtin_convertvector(v, bf16x2_t)); }
; template <int NHQ, int NHKV>
; DI void attn_phase_l1(const u16* __restrict__ Q, const u16* __restrict__ K, const u16* __restrict__ Vt, u16* __restrict__ O, const float* __restrict__ qg, char* smem, const int wv) {
;     ...
;     {
;       const float inv = 1.f / xhalf_sum(l);
;       u16* orow = O + (size_t)(sq * SEQ + pq - NMETA) * DM + hq * 128 + hh * 4;
; #pragma unroll
;       for (int d = 0; d < 4; ++d)
; #pragma unroll
;         for (int q = 0; q < 4; ++q) {
;           u32x2 w = {cvtpk(o[d][4 * q] * inv, o[d][4 * q + 1] * inv), cvtpk(o[d][4 * q + 2] * inv, o[d][4 * q + 3] * inv)};
;           *(u32x2*)(orow + d * 32 + q * 8) = w;
;         }
;     }
	v_fma_f32 v71, -v69, v70, 1.0
	v_fmac_f32_e32 v70, v71, v70
	v_div_scale_f32 v71, vcc, 1.0, v68, 1.0
	s_waitcnt lgkmcnt(2)
	v_mfma_f32_32x32x16_bf16 v[32:47], v[72:75], v[64:67], v[32:47]
	v_mul_f32_e32 v72, v71, v70
	v_fma_f32 v73, -v69, v72, v71
	v_fmac_f32_e32 v72, v73, v70
	v_fma_f32 v69, -v69, v72, v71
	v_div_fmas_f32 v69, v69, v70, v72
	v_lshl_add_u32 v70, s41, 12, v173
	v_ashrrev_i32_e32 v71, 31, v70
	s_waitcnt lgkmcnt(1)
	v_mfma_f32_32x32x16_bf16 v[16:31], v[76:79], v[64:67], v[16:31]
	v_div_fixup_f32 v68, v69, v68, 1.0
	v_mov_b32_e32 v173, v165
	s_waitcnt lgkmcnt(0)
	v_mfma_f32_32x32x16_bf16 v[0:15], v[80:83], v[64:67], v[0:15]
	v_lshlrev_b64 v[64:65], 11, v[70:71]
	v_lshl_add_u64 v[64:65], s[4:5], 0, v[64:65]
	v_lshl_add_u64 v[64:65], s[18:19], 1, v[64:65]
	v_lshl_add_u64 v[64:65], v[64:65], 0, v[172:173]
	v_mbcnt_lo_u32_b32 v66, -1, 0
	v_mbcnt_hi_u32_b32 v66, -1, v66
	v_and_b32_e32 v66, 32, v66
	v_lshrrev_b32_e32 v66, 2, v66
	v_mov_b32_e32 v67, 0
	v_lshl_add_u64 v[64:65], v[64:65], 0, v[66:67]
	v_pk_mul_f32 v[48:49], v[48:49], v[68:69] op_sel_hi:[1,0]
	v_pk_mul_f32 v[50:51], v[50:51], v[68:69] op_sel_hi:[1,0]
	v_pk_mul_f32 v[52:53], v[52:53], v[68:69] op_sel_hi:[1,0]
	v_pk_mul_f32 v[54:55], v[54:55], v[68:69] op_sel_hi:[1,0]
	v_pk_mul_f32 v[56:57], v[56:57], v[68:69] op_sel_hi:[1,0]
	v_pk_mul_f32 v[58:59], v[58:59], v[68:69] op_sel_hi:[1,0]
	v_pk_mul_f32 v[60:61], v[60:61], v[68:69] op_sel_hi:[1,0]
	v_pk_mul_f32 v[62:63], v[62:63], v[68:69] op_sel_hi:[1,0]
	v_cvt_pk_bf16_f32 v48, v48, v49
	v_cvt_pk_bf16_f32 v49, v50, v51
	v_cvt_pk_bf16_f32 v50, v52, v53
	v_cvt_pk_bf16_f32 v51, v54, v55
	v_cvt_pk_bf16_f32 v52, v56, v57
	v_cvt_pk_bf16_f32 v53, v58, v59
	v_cvt_pk_bf16_f32 v54, v60, v61
	v_cvt_pk_bf16_f32 v55, v62, v63
	v_permlane32_swap_b32_e32 v48, v50
	v_permlane32_swap_b32_e32 v49, v51
	v_permlane32_swap_b32_e32 v52, v54
	v_permlane32_swap_b32_e32 v53, v55
	global_store_dwordx4 v[64:65], v[48:51], off
	global_store_dwordx4 v[64:65], v[52:55], off offset:32
	v_pk_mul_f32 v[32:33], v[32:33], v[68:69] op_sel_hi:[1,0]
	v_pk_mul_f32 v[34:35], v[34:35], v[68:69] op_sel_hi:[1,0]
	v_pk_mul_f32 v[36:37], v[36:37], v[68:69] op_sel_hi:[1,0]
	v_pk_mul_f32 v[38:39], v[38:39], v[68:69] op_sel_hi:[1,0]
	v_pk_mul_f32 v[40:41], v[40:41], v[68:69] op_sel_hi:[1,0]
	v_pk_mul_f32 v[42:43], v[42:43], v[68:69] op_sel_hi:[1,0]
	v_pk_mul_f32 v[44:45], v[44:45], v[68:69] op_sel_hi:[1,0]
	v_pk_mul_f32 v[46:47], v[46:47], v[68:69] op_sel_hi:[1,0]
	v_cvt_pk_bf16_f32 v32, v32, v33
	v_cvt_pk_bf16_f32 v33, v34, v35
	v_cvt_pk_bf16_f32 v34, v36, v37
	v_cvt_pk_bf16_f32 v35, v38, v39
	v_cvt_pk_bf16_f32 v36, v40, v41
	v_cvt_pk_bf16_f32 v37, v42, v43
	v_cvt_pk_bf16_f32 v38, v44, v45
	v_cvt_pk_bf16_f32 v39, v46, v47
	v_permlane32_swap_b32_e32 v32, v34
	v_permlane32_swap_b32_e32 v33, v35
	v_permlane32_swap_b32_e32 v36, v38
	v_permlane32_swap_b32_e32 v37, v39
	global_store_dwordx4 v[64:65], v[32:35], off offset:64
	global_store_dwordx4 v[64:65], v[36:39], off offset:96
	v_pk_mul_f32 v[16:17], v[16:17], v[68:69] op_sel_hi:[1,0]
	v_pk_mul_f32 v[18:19], v[18:19], v[68:69] op_sel_hi:[1,0]
	v_pk_mul_f32 v[20:21], v[20:21], v[68:69] op_sel_hi:[1,0]
	v_pk_mul_f32 v[22:23], v[22:23], v[68:69] op_sel_hi:[1,0]
	v_pk_mul_f32 v[24:25], v[24:25], v[68:69] op_sel_hi:[1,0]
	v_pk_mul_f32 v[26:27], v[26:27], v[68:69] op_sel_hi:[1,0]
	v_pk_mul_f32 v[28:29], v[28:29], v[68:69] op_sel_hi:[1,0]
	v_pk_mul_f32 v[30:31], v[30:31], v[68:69] op_sel_hi:[1,0]
	v_cvt_pk_bf16_f32 v16, v16, v17
	v_cvt_pk_bf16_f32 v17, v18, v19
	v_cvt_pk_bf16_f32 v18, v20, v21
	v_cvt_pk_bf16_f32 v19, v22, v23
	v_cvt_pk_bf16_f32 v20, v24, v25
	v_cvt_pk_bf16_f32 v21, v26, v27
	v_cvt_pk_bf16_f32 v22, v28, v29
	v_cvt_pk_bf16_f32 v23, v30, v31
	v_permlane32_swap_b32_e32 v16, v18
	v_permlane32_swap_b32_e32 v17, v19
	v_permlane32_swap_b32_e32 v20, v22
	v_permlane32_swap_b32_e32 v21, v23
	global_store_dwordx4 v[64:65], v[16:19], off offset:128
	global_store_dwordx4 v[64:65], v[20:23], off offset:160
	v_pk_mul_f32 v[0:1], v[0:1], v[68:69] op_sel_hi:[1,0]
	v_pk_mul_f32 v[2:3], v[2:3], v[68:69] op_sel_hi:[1,0]
	v_pk_mul_f32 v[4:5], v[4:5], v[68:69] op_sel_hi:[1,0]
	v_pk_mul_f32 v[6:7], v[6:7], v[68:69] op_sel_hi:[1,0]
	v_pk_mul_f32 v[8:9], v[8:9], v[68:69] op_sel_hi:[1,0]
	v_pk_mul_f32 v[10:11], v[10:11], v[68:69] op_sel_hi:[1,0]
	v_pk_mul_f32 v[12:13], v[12:13], v[68:69] op_sel_hi:[1,0]
	v_pk_mul_f32 v[14:15], v[14:15], v[68:69] op_sel_hi:[1,0]
	v_cvt_pk_bf16_f32 v0, v0, v1
	v_cvt_pk_bf16_f32 v1, v2, v3
	v_cvt_pk_bf16_f32 v2, v4, v5
	v_cvt_pk_bf16_f32 v3, v6, v7
	v_cvt_pk_bf16_f32 v4, v8, v9
	v_cvt_pk_bf16_f32 v5, v10, v11
	v_cvt_pk_bf16_f32 v6, v12, v13
	v_cvt_pk_bf16_f32 v7, v14, v15
	v_permlane32_swap_b32_e32 v0, v2
	v_permlane32_swap_b32_e32 v1, v3
	v_permlane32_swap_b32_e32 v4, v6
	v_permlane32_swap_b32_e32 v5, v7
	global_store_dwordx4 v[64:65], v[0:3], off offset:192
	global_store_dwordx4 v[64:65], v[4:7], off offset:224
	s_add_i32 s28, s28, s12
	s_nop 1
	s_cmpk_gt_i32 s28, 0xbff
	s_cbranch_scc1 .LBB0_1221
